# rwkv tiles: light-prep first LDS reads issued before the next-chunk prefetch code
# speedup vs baseline: 1.0000x; 1.0000x over previous
; template <bool DUAL>
; __device__ __forceinline__ void rwkv_tile(const Params& p, int l, int tile, unsigned char* smem) {
;     ...
;       const int i = (tid >> 4) + 16 * k;
;       const int ri = (d == 0) ? i + 1 : 32 - i;
;       const bf16_t* r0 = raw + ri * 192 + lc;
;       const bf16_t* q0 = pre + (ri - 1) * 192 + lc;
;       float rs[4], ksv[4], vs[4];
; #pragma unroll
;       for (int sl = 0; sl < 3; ++sl) {
;         const uint2 uc = *(const uint2*)(r0 + sl * 64), up = *(const uint2*)(r0 + sl * 64 - 192), un = *(const uint2*)(r0 + sl * 64 + 192);
.LBB0_1411:
	ds_read2_b64 v[60:63], v107 offset1:16
	ds_read_b64 v[72:73], v108
	ds_read2_b64 v[64:67], v107 offset0:32 offset1:48
	ds_read_b64 v[76:77], v109
	ds_read_b64 v[78:79], v110
	ds_read_b64 v[122:123], v111 offset:12928
	ds_read2_b64 v[68:71], v107 offset0:64 offset1:80
	s_add_i32 s52, s28, 1
	s_cmpk_eq_i32 s28, 0x87
	s_cbranch_scc1 .Lrw_du_nopf
	s_lshl_b32 s53, s52, 5
	s_sub_i32 s54, 0x11e0, s53
	s_and_b64 s[50:51], s[36:37], exec
	s_cselect_b32 s53, s53, s54
	s_add_i32 s54, s53, -1
	s_cmpk_eq_u32 s52, 0x87
	s_cbranch_scc1 .Lrw_du_pfslow
	s_and_saveexec_b64 s[50:51], s[42:43]
	v_add_u32_e32 v32, s54, v97
	v_lshlrev_b32_e32 v32, 11, v32
	v_mov_b32_e32 v33, v164
	v_lshl_add_u64 v[32:33], v[80:81], 0, v[32:33]
	global_load_dwordx4 v[32:35], v[32:33], off
	v_add_u32_e32 v28, s54, v98
	v_lshlrev_b32_e32 v28, 11, v28
	v_mov_b32_e32 v29, v164
	v_lshl_add_u64 v[28:29], v[80:81], 0, v[28:29]
	global_load_dwordx4 v[28:31], v[28:29], off
	v_add_u32_e32 v36, s54, v99
	v_lshlrev_b32_e32 v36, 11, v36
	v_mov_b32_e32 v37, v164
	v_lshl_add_u64 v[36:37], v[80:81], 0, v[36:37]
	global_load_dwordx4 v[36:39], v[36:37], off
	v_add_u32_e32 v44, s53, v97
	v_mov_b32_e32 v45, v164
	v_lshlrev_b64 v[44:45], 10, v[44:45]
	v_lshl_add_u64 v[44:45], v[82:83], 0, v[44:45]
	global_load_dwordx4 v[44:47], v[44:45], off
	v_add_u32_e32 v48, s53, v98
	v_mov_b32_e32 v49, v164
	v_lshlrev_b64 v[48:49], 10, v[48:49]
	v_lshl_add_u64 v[48:49], v[82:83], 0, v[48:49]
	global_load_dwordx4 v[48:51], v[48:49], off
	v_add_u32_e32 v52, s53, v99
	v_mov_b32_e32 v53, v164
	v_lshlrev_b64 v[52:53], 10, v[52:53]
	v_lshl_add_u64 v[52:53], v[82:83], 0, v[52:53]
	global_load_dwordx4 v[52:55], v[52:53], off
	s_mov_b64 exec, s[50:51]
	s_and_b64 exec, exec, s[44:45]
	v_add_u32_e32 v40, s54, v100
	v_lshlrev_b32_e32 v40, 11, v40
	v_mov_b32_e32 v41, v164
	v_lshl_add_u64 v[40:41], v[80:81], 0, v[40:41]
	global_load_dwordx4 v[40:43], v[40:41], off
	s_mov_b64 exec, s[50:51]
	s_and_b64 exec, exec, s[46:47]
	v_add_u32_e32 v56, s53, v100
	v_mov_b32_e32 v57, v164
	v_lshlrev_b64 v[56:57], 10, v[56:57]
	v_lshl_add_u64 v[56:57], v[82:83], 0, v[56:57]
	global_load_dwordx4 v[56:59], v[56:57], off
	s_mov_b64 exec, s[50:51]
	s_branch .Lrw_du_nopf

; template <bool DUAL>
; __device__ __forceinline__ void rwkv_tile(const Params& p, int l, int tile, unsigned char* smem) {
;     ...
;       const int i = (tid >> 4) + 16 * k;
;       const int ri = (d == 0) ? i + 1 : 32 - i;
;       const bf16_t* r0 = raw + ri * 192 + lc;
;       const bf16_t* q0 = pre + (ri - 1) * 192 + lc;
;       float rs[4], ksv[4], vs[4];
; #pragma unroll
;       for (int sl = 0; sl < 3; ++sl) {
;         const uint2 uc = *(const uint2*)(r0 + sl * 64), up = *(const uint2*)(r0 + sl * 64 - 192), un = *(const uint2*)(r0 + sl * 64 + 192);
;         const float4 m0 = (sl == 0) ? m0r : ((sl == 1) ? m0k : m0v);
;         const float4 m1 = (sl == 0) ? m1r : ((sl == 1) ? m1k : m1v);
;         float* dst = (sl == 0) ? rs : ((sl == 1) ? ksv : vs);
;         float u, a, n;
;         u = __uint_as_float(uc.x << 16); a = __uint_as_float(up.x << 16); n = __uint_as_float(un.x << 16);
;         dst[0] = u + m0.x * (a - u) + m1.x * (n - u);
;         u = __uint_as_float(uc.x & 0xffff0000u); a = __uint_as_float(up.x & 0xffff0000u); n = __uint_as_float(un.x & 0xffff0000u);
;         dst[1] = u + m0.y * (a - u) + m1.y * (n - u);
;         u = __uint_as_float(uc.y << 16); a = __uint_as_float(up.y << 16); n = __uint_as_float(un.y << 16);
;         dst[2] = u + m0.z * (a - u) + m1.z * (n - u);
;         u = __uint_as_float(uc.y & 0xffff0000u); a = __uint_as_float(up.y & 0xffff0000u); n = __uint_as_float(un.y & 0xffff0000u);
;         dst[3] = u + m0.w * (a - u) + m1.w * (n - u);
;       }
;       const uint2 ue = *(const uint2*)(q0), ua = *(const uint2*)(q0 + 64), uk = *(const uint2*)(q0 + 128);
;       const float ew[4] = {__uint_as_float(ue.x << 16), __uint_as_float(ue.x & 0xffff0000u), __uint_as_float(ue.y << 16), __uint_as_float(ue.y & 0xffff0000u)};
;       const float av[4] = {__uint_as_float(ua.x << 16), __uint_as_float(ua.x & 0xffff0000u), __uint_as_float(ua.y << 16), __uint_as_float(ua.y & 0xffff0000u)};
;       const float kk[4] = {__uint_as_float(uk.x << 16), __uint_as_float(uk.x & 0xffff0000u), __uint_as_float(uk.y << 16), __uint_as_float(uk.y & 0xffff0000u)};
;       const float kav[4] = {ka4.x, ka4.y, ka4.z, ka4.w};
;       float4 o0, o1, o2, o3, o4, o5;
;       float* f0 = (float*)&o0; float* f1 = (float*)&o1; float* f2 = (float*)&o2; float* f3 = (float*)&o3; float* f4 = (float*)&o4; float* f5 = (float*)&o5;
; #pragma unroll
.Lrw_du_nopf:
	s_waitcnt lgkmcnt(6)
	v_lshlrev_b32_e32 v74, 16, v60
	v_and_b32_e32 v75, 0xffff0000, v60
	v_add_u32_e32 v60, 0x3000, v111
	v_lshlrev_b32_e32 v128, 16, v61
	v_and_b32_e32 v129, 0xffff0000, v61
	v_lshlrev_b32_e32 v132, 16, v62
	v_and_b32_e32 v133, 0xffff0000, v62
	v_lshlrev_b32_e32 v138, 16, v63
	v_and_b32_e32 v139, 0xffff0000, v63
	ds_read2_b64 v[60:63], v60 offset0:48 offset1:64
	s_waitcnt lgkmcnt(5)
	v_lshlrev_b32_e32 v142, 16, v64
	v_and_b32_e32 v143, 0xffff0000, v64
	s_waitcnt lgkmcnt(1)
	v_lshlrev_b32_e32 v136, 16, v68
	v_and_b32_e32 v137, 0xffff0000, v68
	s_waitcnt lgkmcnt(0)
	v_lshlrev_b32_e32 v64, 16, v60
	v_and_b32_e32 v60, 0xffff0000, v60
	v_lshlrev_b32_e32 v68, 16, v61
	v_mul_f32_e32 v60, 0xbfb8aa3b, v60
	v_lshlrev_b32_e32 v130, 16, v67
	v_and_b32_e32 v131, 0xffff0000, v67
	v_and_b32_e32 v61, 0xffff0000, v61
	v_exp_f32_e32 v67, v60
	v_mul_f32_e32 v60, 0xbfb8aa3b, v68
	v_mul_f32_e32 v64, 0xbfb8aa3b, v64
	v_exp_f32_e32 v68, v60
	v_mul_f32_e32 v60, 0xbfb8aa3b, v61
	v_lshlrev_b32_e32 v126, 16, v66
	v_and_b32_e32 v127, 0xffff0000, v66
	v_lshlrev_b32_e32 v140, 16, v69
	v_and_b32_e32 v141, 0xffff0000, v69
	v_exp_f32_e32 v66, v64
	v_exp_f32_e32 v69, v60
	v_lshlrev_b32_e32 v121, 16, v62
	v_lshlrev_b32_e32 v150, 16, v123
	v_lshlrev_b32_e32 v153, 16, v63
	ds_write_b128 v119, v[66:69] offset:25344
	v_and_b32_e32 v67, 16, v62
	v_and_b32_e32 v66, 0xffff0000, v122
	v_lshlrev_b32_e32 v68, 16, v122
	v_and_b32_e32 v69, 0xffff0000, v62
	v_pk_mov_b32 v[60:61], v[120:121], v[66:67] op_sel:[1,0]
	v_and_b32_e32 v155, 16, v63
	v_and_b32_e32 v154, 0xffff0000, v123
	v_lshlrev_b32_e32 v134, 16, v76
	v_and_b32_e32 v135, 0xffff0000, v76
	v_lshlrev_b32_e32 v148, 16, v65
	v_and_b32_e32 v149, 0xffff0000, v65
	v_pk_mul_f32 v[60:61], v[68:69], v[60:61]
	v_and_b32_e32 v151, 0xffff0000, v63
	v_pk_mov_b32 v[62:63], v[152:153], v[154:155] op_sel:[1,0]
	v_mov_b32_e32 v64, v68
	v_mov_b32_e32 v65, v66
	v_mov_b32_e32 v66, v150
	v_mov_b32_e32 v67, v154
	v_pk_mul_f32 v[62:63], v[150:151], v[62:63]
	ds_write_b128 v119, v[64:67] offset:25600
	ds_write_b128 v119, v[60:63] offset:25856
	v_pk_add_f32 v[60:61], v[134:135], v[132:133] neg_lo:[0,1] neg_hi:[0,1]
	v_pk_add_f32 v[62:63], v[136:137], v[132:133] neg_lo:[0,1] neg_hi:[0,1]

; template <bool DUAL>
; __device__ __forceinline__ void rwkv_tile(const Params& p, int l, int tile, unsigned char* smem) {
;     ...
;         dst[0] = u + m0.x * (a - u) + m1.x * (n - u);
;         u = __uint_as_float(uc.x & 0xffff0000u); a = __uint_as_float(up.x & 0xffff0000u); n = __uint_as_float(un.x & 0xffff0000u);
;         dst[1] = u + m0.y * (a - u) + m1.y * (n - u);
;         u = __uint_as_float(uc.y << 16); a = __uint_as_float(up.y << 16); n = __uint_as_float(un.y << 16);
;         dst[2] = u + m0.z * (a - u) + m1.z * (n - u);
	v_pk_fma_f32 v[60:61], v[12:13], v[60:61], v[132:133]
	v_mov_b32_e32 v68, v121

; template <bool DUAL>
; __device__ __forceinline__ void rwkv_tile(const Params& p, int l, int tile, unsigned char* smem) {
;     ...
;         dst[0] = u + m0.x * (a - u) + m1.x * (n - u);
;         u = __uint_as_float(uc.x & 0xffff0000u); a = __uint_as_float(up.x & 0xffff0000u); n = __uint_as_float(un.x & 0xffff0000u);
;         dst[1] = u + m0.y * (a - u) + m1.y * (n - u);
;         u = __uint_as_float(uc.y << 16); a = __uint_as_float(up.y << 16); n = __uint_as_float(un.y << 16);
;         dst[2] = u + m0.z * (a - u) + m1.z * (n - u);
;         u = __uint_as_float(uc.y & 0xffff0000u); a = __uint_as_float(up.y & 0xffff0000u); n = __uint_as_float(un.y & 0xffff0000u);
;         dst[3] = u + m0.w * (a - u) + m1.w * (n - u);
;       }
;       const uint2 ue = *(const uint2*)(q0), ua = *(const uint2*)(q0 + 64), uk = *(const uint2*)(q0 + 128);
;       const float ew[4] = {__uint_as_float(ue.x << 16), __uint_as_float(ue.x & 0xffff0000u), __uint_as_float(ue.y << 16), __uint_as_float(ue.y & 0xffff0000u)};
;       const float av[4] = {__uint_as_float(ua.x << 16), __uint_as_float(ua.x & 0xffff0000u), __uint_as_float(ua.y << 16), __uint_as_float(ua.y & 0xffff0000u)};
;       const float kk[4] = {__uint_as_float(uk.x << 16), __uint_as_float(uk.x & 0xffff0000u), __uint_as_float(uk.y << 16), __uint_as_float(uk.y & 0xffff0000u)};
;       const float kav[4] = {ka4.x, ka4.y, ka4.z, ka4.w};
;       float4 o0, o1, o2, o3, o4, o5;
;       float* f0 = (float*)&o0; float* f1 = (float*)&o1; float* f2 = (float*)&o2; float* f3 = (float*)&o3; float* f4 = (float*)&o4; float* f5 = (float*)&o5;
; #pragma unroll
;       for (int e = 0; e < 4; ++e) {
;         f0[e] = __expf(-ew[e]);
;         f1[e] = kk[e];
;         f2[e] = kk[e] * av[e];
;         f3[e] = ksv[e] * (1.f + (av[e] - 1.f) * kav[e]);
	v_pk_fma_f32 v[60:61], v[20:21], v[62:63], v[60:61]
	v_pk_add_f32 v[62:63], v[68:69], -1.0 op_sel_hi:[1,0]
	v_lshlrev_b32_e32 v76, 16, v77
	v_and_b32_e32 v77, 0xffff0000, v77

; template <bool DUAL>
; __device__ __forceinline__ void rwkv_tile(const Params& p, int l, int tile, unsigned char* smem) {
;     ...
;         dst[0] = u + m0.x * (a - u) + m1.x * (n - u);
;         u = __uint_as_float(uc.x & 0xffff0000u); a = __uint_as_float(up.x & 0xffff0000u); n = __uint_as_float(un.x & 0xffff0000u);
;         dst[1] = u + m0.y * (a - u) + m1.y * (n - u);
;         u = __uint_as_float(uc.y << 16); a = __uint_as_float(up.y << 16); n = __uint_as_float(un.y << 16);
;         dst[2] = u + m0.z * (a - u) + m1.z * (n - u);
;         u = __uint_as_float(uc.y & 0xffff0000u); a = __uint_as_float(up.y & 0xffff0000u); n = __uint_as_float(un.y & 0xffff0000u);
;         dst[3] = u + m0.w * (a - u) + m1.w * (n - u);
;       }
;       const uint2 ue = *(const uint2*)(q0), ua = *(const uint2*)(q0 + 64), uk = *(const uint2*)(q0 + 128);
;       const float ew[4] = {__uint_as_float(ue.x << 16), __uint_as_float(ue.x & 0xffff0000u), __uint_as_float(ue.y << 16), __uint_as_float(ue.y & 0xffff0000u)};
;       const float av[4] = {__uint_as_float(ua.x << 16), __uint_as_float(ua.x & 0xffff0000u), __uint_as_float(ua.y << 16), __uint_as_float(ua.y & 0xffff0000u)};
;       const float kk[4] = {__uint_as_float(uk.x << 16), __uint_as_float(uk.x & 0xffff0000u), __uint_as_float(uk.y << 16), __uint_as_float(uk.y & 0xffff0000u)};
;       const float kav[4] = {ka4.x, ka4.y, ka4.z, ka4.w};
;       float4 o0, o1, o2, o3, o4, o5;
;       float* f0 = (float*)&o0; float* f1 = (float*)&o1; float* f2 = (float*)&o2; float* f3 = (float*)&o3; float* f4 = (float*)&o4; float* f5 = (float*)&o5;
; #pragma unroll
;       for (int e = 0; e < 4; ++e) {
;         f0[e] = __expf(-ew[e]);
;         f1[e] = kk[e];
;         f2[e] = kk[e] * av[e];
;         f3[e] = ksv[e] * (1.f + (av[e] - 1.f) * kav[e]);
;         f4[e] = rs[e];
;         f5[e] = vs[e];
;       }
;       float* rp = rec + i * 384 + lc;
;       *(float4*)(rp) = o0; *(float4*)(rp + 64) = o1; *(float4*)(rp + 128) = o2;
;       *(float4*)(rp + 192) = o3; *(float4*)(rp + 256) = o4; *(float4*)(rp + 320) = o5;
	v_pk_fma_f32 v[62:63], v[24:25], v[62:63], 1.0 op_sel_hi:[1,1,0]
	v_pk_add_f32 v[64:65], v[140:141], v[138:139] neg_lo:[0,1] neg_hi:[0,1]
	v_pk_mul_f32 v[60:61], v[60:61], v[62:63]
	v_pk_add_f32 v[62:63], v[76:77], v[138:139] neg_lo:[0,1] neg_hi:[0,1]
	v_mov_b32_e32 v150, v153
	v_pk_fma_f32 v[62:63], v[14:15], v[62:63], v[138:139]
	v_lshlrev_b32_e32 v124, 16, v72
	v_pk_fma_f32 v[62:63], v[22:23], v[64:65], v[62:63]
	v_pk_add_f32 v[64:65], v[150:151], -1.0 op_sel_hi:[1,0]
	v_and_b32_e32 v125, 0xffff0000, v72
	v_pk_fma_f32 v[64:65], v[26:27], v[64:65], 1.0 op_sel_hi:[1,1,0]
	v_lshlrev_b32_e32 v72, 16, v73
	v_pk_mul_f32 v[62:63], v[62:63], v[64:65]
	ds_write_b128 v119, v[60:63] offset:26112
	v_pk_add_f32 v[60:61], v[124:125], v[74:75] neg_lo:[0,1] neg_hi:[0,1]
	v_and_b32_e32 v73, 0xffff0000, v73
	v_pk_fma_f32 v[60:61], v[8:9], v[60:61], v[74:75]
	v_pk_add_f32 v[62:63], v[126:127], v[74:75] neg_lo:[0,1] neg_hi:[0,1]
	v_pk_add_f32 v[64:65], v[130:131], v[128:129] neg_lo:[0,1] neg_hi:[0,1]
	v_pk_fma_f32 v[60:61], v[0:1], v[62:63], v[60:61]
	v_pk_add_f32 v[62:63], v[72:73], v[128:129] neg_lo:[0,1] neg_hi:[0,1]
	v_lshlrev_b32_e32 v144, 16, v78
	v_pk_fma_f32 v[62:63], v[10:11], v[62:63], v[128:129]
	v_and_b32_e32 v145, 0xffff0000, v78
	v_pk_fma_f32 v[62:63], v[2:3], v[64:65], v[62:63]
	v_lshlrev_b32_e32 v146, 16, v70
	v_and_b32_e32 v147, 0xffff0000, v70
	ds_write_b128 v119, v[60:63] offset:26368
	v_pk_add_f32 v[60:61], v[144:145], v[142:143] neg_lo:[0,1] neg_hi:[0,1]
	v_lshlrev_b32_e32 v78, 16, v79
	v_and_b32_e32 v79, 0xffff0000, v79
	v_pk_fma_f32 v[60:61], v[4:5], v[60:61], v[142:143]
	v_pk_add_f32 v[62:63], v[146:147], v[142:143] neg_lo:[0,1] neg_hi:[0,1]
	v_lshlrev_b32_e32 v70, 16, v71
	v_and_b32_e32 v71, 0xffff0000, v71
	v_pk_fma_f32 v[60:61], v[16:17], v[62:63], v[60:61]
	v_pk_add_f32 v[62:63], v[78:79], v[148:149] neg_lo:[0,1] neg_hi:[0,1]
	v_pk_add_f32 v[64:65], v[70:71], v[148:149] neg_lo:[0,1] neg_hi:[0,1]
	v_pk_fma_f32 v[62:63], v[6:7], v[62:63], v[148:149]
	s_add_i32 s52, s28, 1
	v_pk_fma_f32 v[62:63], v[18:19], v[64:65], v[62:63]
	ds_write_b128 v119, v[60:63] offset:26624
	ds_read2_b64 v[60:63], v112 offset1:16
	ds_read_b64 v[72:73], v113
	ds_read2_b64 v[64:67], v112 offset0:32 offset1:48
	ds_read_b64 v[76:77], v114
	ds_read_b64 v[78:79], v115
	ds_read_b64 v[122:123], v116 offset:12928
	ds_read2_b64 v[68:71], v112 offset0:64 offset1:80
	s_waitcnt lgkmcnt(6)
	v_lshlrev_b32_e32 v74, 16, v60
	v_and_b32_e32 v75, 0xffff0000, v60
	v_add_u32_e32 v60, 0x3000, v116
	v_lshlrev_b32_e32 v128, 16, v61
	v_and_b32_e32 v129, 0xffff0000, v61
	v_lshlrev_b32_e32 v132, 16, v62
	v_and_b32_e32 v133, 0xffff0000, v62
	v_lshlrev_b32_e32 v138, 16, v63
	v_and_b32_e32 v139, 0xffff0000, v63
	ds_read2_b64 v[60:63], v60 offset0:48 offset1:64
	s_waitcnt lgkmcnt(5)
	v_lshlrev_b32_e32 v142, 16, v64
	v_and_b32_e32 v143, 0xffff0000, v64
	s_waitcnt lgkmcnt(1)
	v_lshlrev_b32_e32 v136, 16, v68
	v_and_b32_e32 v137, 0xffff0000, v68
	s_waitcnt lgkmcnt(0)
; template <bool DUAL>
; __device__ __forceinline__ void rwkv_tile(const Params& p, int l, int tile, unsigned char* smem) {
;     ...
;     for (int k = 0; k < 2; ++k) {
;       const int i = (tid >> 4) + 16 * k;
;       const int ri = (d == 0) ? i + 1 : 32 - i;
;       const bf16_t* r0 = raw + ri * 192 + lc;
;       const bf16_t* q0 = pre + (ri - 1) * 192 + lc;
;       float rs[4], ksv[4], vs[4];
; #pragma unroll
;       for (int sl = 0; sl < 3; ++sl) {
;         const uint2 uc = *(const uint2*)(r0 + sl * 64), up = *(const uint2*)(r0 + sl * 64 - 192), un = *(const uint2*)(r0 + sl * 64 + 192);
;         const float4 m0 = (sl == 0) ? m0r : ((sl == 1) ? m0k : m0v);
;         const float4 m1 = (sl == 0) ? m1r : ((sl == 1) ? m1k : m1v);
;         float* dst = (sl == 0) ? rs : ((sl == 1) ? ksv : vs);
;         float u, a, n;
;         u = __uint_as_float(uc.x << 16); a = __uint_as_float(up.x << 16); n = __uint_as_float(un.x << 16);
;         dst[0] = u + m0.x * (a - u) + m1.x * (n - u);
;         u = __uint_as_float(uc.x & 0xffff0000u); a = __uint_as_float(up.x & 0xffff0000u); n = __uint_as_float(un.x & 0xffff0000u);
;         dst[1] = u + m0.y * (a - u) + m1.y * (n - u);
;         u = __uint_as_float(uc.y << 16); a = __uint_as_float(up.y << 16); n = __uint_as_float(un.y << 16);
;         dst[2] = u + m0.z * (a - u) + m1.z * (n - u);
;         u = __uint_as_float(uc.y & 0xffff0000u); a = __uint_as_float(up.y & 0xffff0000u); n = __uint_as_float(un.y & 0xffff0000u);
;         dst[3] = u + m0.w * (a - u) + m1.w * (n - u);
;       }
;       const uint2 ue = *(const uint2*)(q0), ua = *(const uint2*)(q0 + 64), uk = *(const uint2*)(q0 + 128);
;       const float ew[4] = {__uint_as_float(ue.x << 16), __uint_as_float(ue.x & 0xffff0000u), __uint_as_float(ue.y << 16), __uint_as_float(ue.y & 0xffff0000u)};
;       const float av[4] = {__uint_as_float(ua.x << 16), __uint_as_float(ua.x & 0xffff0000u), __uint_as_float(ua.y << 16), __uint_as_float(ua.y & 0xffff0000u)};
;       const float kk[4] = {__uint_as_float(uk.x << 16), __uint_as_float(uk.x & 0xffff0000u), __uint_as_float(uk.y << 16), __uint_as_float(uk.y & 0xffff0000u)};
;       const float kav[4] = {ka4.x, ka4.y, ka4.z, ka4.w};
;       float4 o0, o1, o2, o3, o4, o5;
;       float* f0 = (float*)&o0; float* f1 = (float*)&o1; float* f2 = (float*)&o2; float* f3 = (float*)&o3; float* f4 = (float*)&o4; float* f5 = (float*)&o5;
	v_lshlrev_b32_e32 v64, 16, v60
	v_and_b32_e32 v60, 0xffff0000, v60
	v_lshlrev_b32_e32 v68, 16, v61
	v_mul_f32_e32 v60, 0xbfb8aa3b, v60
	v_lshlrev_b32_e32 v130, 16, v67
	v_and_b32_e32 v131, 0xffff0000, v67
	v_and_b32_e32 v61, 0xffff0000, v61
	v_exp_f32_e32 v67, v60
	v_mul_f32_e32 v60, 0xbfb8aa3b, v68
	v_mul_f32_e32 v64, 0xbfb8aa3b, v64
	v_exp_f32_e32 v68, v60
	v_mul_f32_e32 v60, 0xbfb8aa3b, v61
	v_lshlrev_b32_e32 v126, 16, v66
	v_and_b32_e32 v127, 0xffff0000, v66
	v_lshlrev_b32_e32 v140, 16, v69
	v_and_b32_e32 v141, 0xffff0000, v69
	v_exp_f32_e32 v66, v64
	v_exp_f32_e32 v69, v60
	v_lshlrev_b32_e32 v121, 16, v62
	v_lshlrev_b32_e32 v150, 16, v123
	v_lshlrev_b32_e32 v153, 16, v63
	ds_write_b128 v119, v[66:69] offset:49920
	v_and_b32_e32 v67, 16, v62
	v_and_b32_e32 v66, 0xffff0000, v122
	v_lshlrev_b32_e32 v68, 16, v122
	v_and_b32_e32 v69, 0xffff0000, v62
	v_pk_mov_b32 v[60:61], v[120:121], v[66:67] op_sel:[1,0]
	v_and_b32_e32 v155, 16, v63
	v_and_b32_e32 v154, 0xffff0000, v123
	v_lshlrev_b32_e32 v134, 16, v76
	v_and_b32_e32 v135, 0xffff0000, v76
	v_lshlrev_b32_e32 v148, 16, v65
	v_and_b32_e32 v149, 0xffff0000, v65
	v_pk_mul_f32 v[60:61], v[68:69], v[60:61]
	v_and_b32_e32 v151, 0xffff0000, v63
	v_pk_mov_b32 v[62:63], v[152:153], v[154:155] op_sel:[1,0]
	v_mov_b32_e32 v64, v68
	v_mov_b32_e32 v65, v66
	v_mov_b32_e32 v66, v150
	v_mov_b32_e32 v67, v154
	v_pk_mul_f32 v[62:63], v[150:151], v[62:63]
	ds_write_b128 v119, v[64:67] offset:50176
	ds_write_b128 v119, v[60:63] offset:50432
	v_pk_add_f32 v[60:61], v[134:135], v[132:133] neg_lo:[0,1] neg_hi:[0,1]
	v_pk_add_f32 v[62:63], v[136:137], v[132:133] neg_lo:[0,1] neg_hi:[0,1]
	v_pk_fma_f32 v[60:61], v[12:13], v[60:61], v[132:133]
	v_mov_b32_e32 v68, v121
	v_pk_fma_f32 v[60:61], v[20:21], v[62:63], v[60:61]
	v_pk_add_f32 v[62:63], v[68:69], -1.0 op_sel_hi:[1,0]
	v_lshlrev_b32_e32 v76, 16, v77
	v_and_b32_e32 v77, 0xffff0000, v77
	v_pk_fma_f32 v[62:63], v[24:25], v[62:63], 1.0 op_sel_hi:[1,1,0]
	v_pk_add_f32 v[64:65], v[140:141], v[138:139] neg_lo:[0,1] neg_hi:[0,1]
	v_pk_mul_f32 v[60:61], v[60:61], v[62:63]
	v_pk_add_f32 v[62:63], v[76:77], v[138:139] neg_lo:[0,1] neg_hi:[0,1]
	v_mov_b32_e32 v150, v153
	v_pk_fma_f32 v[62:63], v[14:15], v[62:63], v[138:139]
	v_lshlrev_b32_e32 v124, 16, v72
	v_pk_fma_f32 v[62:63], v[22:23], v[64:65], v[62:63]
	v_pk_add_f32 v[64:65], v[150:151], -1.0 op_sel_hi:[1,0]
	v_and_b32_e32 v125, 0xffff0000, v72
	v_pk_fma_f32 v[64:65], v[26:27], v[64:65], 1.0 op_sel_hi:[1,1,0]
	v_lshlrev_b32_e32 v72, 16, v73
	v_pk_mul_f32 v[62:63], v[62:63], v[64:65]
	ds_write_b128 v119, v[60:63] offset:50688
	v_pk_add_f32 v[60:61], v[124:125], v[74:75] neg_lo:[0,1] neg_hi:[0,1]
	v_and_b32_e32 v73, 0xffff0000, v73
	v_pk_fma_f32 v[60:61], v[8:9], v[60:61], v[74:75]
	v_pk_add_f32 v[62:63], v[126:127], v[74:75] neg_lo:[0,1] neg_hi:[0,1]
	v_pk_add_f32 v[64:65], v[130:131], v[128:129] neg_lo:[0,1] neg_hi:[0,1]
	v_pk_fma_f32 v[60:61], v[0:1], v[62:63], v[60:61]
	v_pk_add_f32 v[62:63], v[72:73], v[128:129] neg_lo:[0,1] neg_hi:[0,1]
	v_lshlrev_b32_e32 v144, 16, v78
	v_pk_fma_f32 v[62:63], v[10:11], v[62:63], v[128:129]
	v_and_b32_e32 v145, 0xffff0000, v78
	v_pk_fma_f32 v[62:63], v[2:3], v[64:65], v[62:63]
	v_lshlrev_b32_e32 v146, 16, v70
	v_and_b32_e32 v147, 0xffff0000, v70
	ds_write_b128 v119, v[60:63] offset:50944
	v_pk_add_f32 v[60:61], v[144:145], v[142:143] neg_lo:[0,1] neg_hi:[0,1]
	v_lshlrev_b32_e32 v78, 16, v79
	v_and_b32_e32 v79, 0xffff0000, v79
	v_pk_fma_f32 v[60:61], v[4:5], v[60:61], v[142:143]
	v_pk_add_f32 v[62:63], v[146:147], v[142:143] neg_lo:[0,1] neg_hi:[0,1]
	v_lshlrev_b32_e32 v70, 16, v71
	v_and_b32_e32 v71, 0xffff0000, v71
	v_pk_fma_f32 v[60:61], v[16:17], v[62:63], v[60:61]
	v_pk_add_f32 v[62:63], v[78:79], v[148:149] neg_lo:[0,1] neg_hi:[0,1]
	v_pk_add_f32 v[64:65], v[70:71], v[148:149] neg_lo:[0,1] neg_hi:[0,1]
	v_pk_fma_f32 v[62:63], v[6:7], v[62:63], v[148:149]
	s_cmpk_lg_i32 s28, 0x87
	v_pk_fma_f32 v[62:63], v[18:19], v[64:65], v[62:63]
	s_cselect_b64 s[48:49], -1, 0
	s_cmpk_eq_i32 s28, 0x87
	ds_write_b128 v119, v[60:63] offset:51200
	s_waitcnt lgkmcnt(0)
	s_barrier

; template <bool DUAL>
; __device__ __forceinline__ void rwkv_tile(const Params& p, int l, int tile, unsigned char* smem) {
;     ...
;       const int i = (tid >> 4) + 16 * k;
;       const int ri = (d == 0) ? i + 1 : 32 - i;
;       const bf16_t* r0 = raw + ri * 192 + lc;
;       const bf16_t* q0 = pre + (ri - 1) * 192 + lc;
;       float rs[4], ksv[4], vs[4];
; #pragma unroll
;       for (int sl = 0; sl < 3; ++sl) {
;         const uint2 uc = *(const uint2*)(r0 + sl * 64), up = *(const uint2*)(r0 + sl * 64 - 192), un = *(const uint2*)(r0 + sl * 64 + 192);
.LBB0_1468:
	ds_read2_b64 v[64:67], v104 offset1:16
	ds_read_b64 v[76:77], v105
	ds_read2_b64 v[68:71], v104 offset0:32 offset1:48
	ds_read_b64 v[80:81], v106
	ds_read_b64 v[82:83], v107
	ds_read_b64 v[118:119], v108 offset:12928
	ds_read2_b64 v[72:75], v104 offset0:64 offset1:80
	s_add_i32 s56, s28, 1
	v_readlane_b32 s0, v254, 14
	s_cmp_ge_u32 s56, s0
	s_cbranch_scc1 .Lrw_nd_nopf
	s_lshl_b32 s57, s56, 5
	s_sub_i32 s58, 0xe0, s57
	s_and_b64 s[50:51], s[36:37], exec
	s_cselect_b32 s64, s57, s58
	s_sub_i32 s58, 0x11e0, s57
	s_and_b64 s[50:51], s[36:37], exec
	s_cselect_b32 s50, s57, s58
	s_cmp_lt_u32 s28, 7
	s_movk_i32 s0, 0x10ff
	s_cselect_b32 s57, s64, s50
	s_cselect_b32 s58, 0xff, s0
	s_cselect_b32 s59, 0, 0x100
	s_add_i32 s66, s57, -1
	s_cmp_eq_u32 s56, 7
	s_cbranch_scc1 .Lrw_nd_pfslow
	s_cmp_eq_u32 s56, 8
	s_cbranch_scc1 .Lrw_nd_pfslow
	s_cmpk_eq_u32 s56, 0x87
	s_cbranch_scc1 .Lrw_nd_pfslow
	s_and_saveexec_b64 s[50:51], s[42:43]
	v_add_u32_e32 v32, s66, v93
	v_lshlrev_b32_e32 v32, 11, v32
	v_mov_b32_e32 v33, v164
	v_lshl_add_u64 v[32:33], v[84:85], 0, v[32:33]
	global_load_dwordx4 v[32:35], v[32:33], off
	v_add_u32_e32 v28, s66, v94
	v_lshlrev_b32_e32 v28, 11, v28
	v_mov_b32_e32 v29, v164
	v_lshl_add_u64 v[28:29], v[84:85], 0, v[28:29]
	global_load_dwordx4 v[28:31], v[28:29], off
	v_add_u32_e32 v36, s66, v95
	v_lshlrev_b32_e32 v36, 11, v36
	v_mov_b32_e32 v37, v164
	v_lshl_add_u64 v[36:37], v[84:85], 0, v[36:37]
	global_load_dwordx4 v[36:39], v[36:37], off
	v_add_u32_e32 v44, s57, v93
	v_mov_b32_e32 v45, v164
	v_lshlrev_b64 v[44:45], 10, v[44:45]
	v_lshl_add_u64 v[44:45], v[86:87], 0, v[44:45]
	global_load_dwordx4 v[44:47], v[44:45], off
	v_add_u32_e32 v48, s57, v94
	v_mov_b32_e32 v49, v164
	v_lshlrev_b64 v[48:49], 10, v[48:49]
	v_lshl_add_u64 v[48:49], v[86:87], 0, v[48:49]
	global_load_dwordx4 v[48:51], v[48:49], off
	v_add_u32_e32 v52, s57, v95
	v_mov_b32_e32 v53, v164
	v_lshlrev_b64 v[52:53], 10, v[52:53]
	v_lshl_add_u64 v[52:53], v[86:87], 0, v[52:53]
	global_load_dwordx4 v[52:55], v[52:53], off
	s_mov_b64 exec, s[50:51]
	s_andn2_b64 exec, exec, s[46:47]
	v_add_u32_e32 v40, s66, v96
	v_lshlrev_b32_e32 v40, 11, v40
	v_mov_b32_e32 v41, v164
	v_lshl_add_u64 v[40:41], v[84:85], 0, v[40:41]
	global_load_dwordx4 v[40:43], v[40:41], off
	s_mov_b64 exec, s[50:51]
	s_and_b64 exec, exec, s[48:49]
	v_add_u32_e32 v56, s57, v96
	v_mov_b32_e32 v57, v164
	v_lshlrev_b64 v[56:57], 10, v[56:57]
	v_lshl_add_u64 v[56:57], v[86:87], 0, v[56:57]
	global_load_dwordx4 v[56:59], v[56:57], off
	s_mov_b64 exec, s[50:51]
	s_branch .Lrw_nd_nopf

; template <bool DUAL>
; __device__ __forceinline__ void rwkv_tile(const Params& p, int l, int tile, unsigned char* smem) {
;     ...
;       const int i = (tid >> 4) + 16 * k;
;       const int ri = (d == 0) ? i + 1 : 32 - i;
;       const bf16_t* r0 = raw + ri * 192 + lc;
;       const bf16_t* q0 = pre + (ri - 1) * 192 + lc;
;       float rs[4], ksv[4], vs[4];
; #pragma unroll
;       for (int sl = 0; sl < 3; ++sl) {
;         const uint2 uc = *(const uint2*)(r0 + sl * 64), up = *(const uint2*)(r0 + sl * 64 - 192), un = *(const uint2*)(r0 + sl * 64 + 192);
;         const float4 m0 = (sl == 0) ? m0r : ((sl == 1) ? m0k : m0v);
;         const float4 m1 = (sl == 0) ? m1r : ((sl == 1) ? m1k : m1v);
;         float* dst = (sl == 0) ? rs : ((sl == 1) ? ksv : vs);
;         float u, a, n;
;         u = __uint_as_float(uc.x << 16); a = __uint_as_float(up.x << 16); n = __uint_as_float(un.x << 16);
;         dst[0] = u + m0.x * (a - u) + m1.x * (n - u);
;         u = __uint_as_float(uc.x & 0xffff0000u); a = __uint_as_float(up.x & 0xffff0000u); n = __uint_as_float(un.x & 0xffff0000u);
;         dst[1] = u + m0.y * (a - u) + m1.y * (n - u);
;         u = __uint_as_float(uc.y << 16); a = __uint_as_float(up.y << 16); n = __uint_as_float(un.y << 16);
;         dst[2] = u + m0.z * (a - u) + m1.z * (n - u);
;         u = __uint_as_float(uc.y & 0xffff0000u); a = __uint_as_float(up.y & 0xffff0000u); n = __uint_as_float(un.y & 0xffff0000u);
;         dst[3] = u + m0.w * (a - u) + m1.w * (n - u);
;       }
;       const uint2 ue = *(const uint2*)(q0), ua = *(const uint2*)(q0 + 64), uk = *(const uint2*)(q0 + 128);
;       const float ew[4] = {__uint_as_float(ue.x << 16), __uint_as_float(ue.x & 0xffff0000u), __uint_as_float(ue.y << 16), __uint_as_float(ue.y & 0xffff0000u)};
;       const float av[4] = {__uint_as_float(ua.x << 16), __uint_as_float(ua.x & 0xffff0000u), __uint_as_float(ua.y << 16), __uint_as_float(ua.y & 0xffff0000u)};
;       const float kk[4] = {__uint_as_float(uk.x << 16), __uint_as_float(uk.x & 0xffff0000u), __uint_as_float(uk.y << 16), __uint_as_float(uk.y & 0xffff0000u)};
;       const float kav[4] = {ka4.x, ka4.y, ka4.z, ka4.w};
;       float4 o0, o1, o2, o3, o4, o5;
;       float* f0 = (float*)&o0; float* f1 = (float*)&o1; float* f2 = (float*)&o2; float* f3 = (float*)&o3; float* f4 = (float*)&o4; float* f5 = (float*)&o5;
; #pragma unroll
.Lrw_nd_nopf:
	s_waitcnt lgkmcnt(6)
	v_lshlrev_b32_e32 v78, 16, v64
	v_and_b32_e32 v79, 0xffff0000, v64
	v_add_u32_e32 v64, 0x3000, v108
	v_lshlrev_b32_e32 v124, 16, v65
	v_and_b32_e32 v125, 0xffff0000, v65
	v_lshlrev_b32_e32 v128, 16, v66
	v_and_b32_e32 v129, 0xffff0000, v66
	v_lshlrev_b32_e32 v134, 16, v67
	v_and_b32_e32 v135, 0xffff0000, v67
	ds_read2_b64 v[64:67], v64 offset0:48 offset1:64
	s_waitcnt lgkmcnt(5)
	v_lshlrev_b32_e32 v138, 16, v68
	v_and_b32_e32 v139, 0xffff0000, v68
	s_waitcnt lgkmcnt(1)
	v_lshlrev_b32_e32 v132, 16, v72
	v_and_b32_e32 v133, 0xffff0000, v72
	s_waitcnt lgkmcnt(0)
	v_lshlrev_b32_e32 v68, 16, v64
	v_and_b32_e32 v64, 0xffff0000, v64
	v_lshlrev_b32_e32 v72, 16, v65
	v_mul_f32_e32 v64, 0xbfb8aa3b, v64
	v_lshlrev_b32_e32 v126, 16, v71
	v_and_b32_e32 v127, 0xffff0000, v71
	v_and_b32_e32 v65, 0xffff0000, v65
	v_exp_f32_e32 v71, v64
	v_mul_f32_e32 v64, 0xbfb8aa3b, v72
	v_mul_f32_e32 v68, 0xbfb8aa3b, v68
	v_exp_f32_e32 v72, v64
	v_mul_f32_e32 v64, 0xbfb8aa3b, v65
	v_lshlrev_b32_e32 v122, 16, v70
	v_and_b32_e32 v123, 0xffff0000, v70
	v_lshlrev_b32_e32 v136, 16, v73
	v_and_b32_e32 v137, 0xffff0000, v73
	v_exp_f32_e32 v70, v68
	v_exp_f32_e32 v73, v64
	v_lshlrev_b32_e32 v117, 16, v66
	v_lshlrev_b32_e32 v146, 16, v119
	v_lshlrev_b32_e32 v149, 16, v67
	ds_write_b128 v115, v[70:73] offset:25344
	v_and_b32_e32 v71, 16, v66
	v_and_b32_e32 v70, 0xffff0000, v118
	v_lshlrev_b32_e32 v72, 16, v118
	v_and_b32_e32 v73, 0xffff0000, v66
	v_pk_mov_b32 v[64:65], v[116:117], v[70:71] op_sel:[1,0]
	v_and_b32_e32 v151, 16, v67
	v_and_b32_e32 v150, 0xffff0000, v119
	v_lshlrev_b32_e32 v130, 16, v80
	v_and_b32_e32 v131, 0xffff0000, v80
	v_lshlrev_b32_e32 v144, 16, v69
	v_and_b32_e32 v145, 0xffff0000, v69
	v_pk_mul_f32 v[64:65], v[72:73], v[64:65]
	v_and_b32_e32 v147, 0xffff0000, v67
	v_pk_mov_b32 v[66:67], v[148:149], v[150:151] op_sel:[1,0]
	v_mov_b32_e32 v68, v72
	v_mov_b32_e32 v69, v70
	v_mov_b32_e32 v70, v146
	v_mov_b32_e32 v71, v150
	v_pk_mul_f32 v[66:67], v[146:147], v[66:67]
	ds_write_b128 v115, v[68:71] offset:25600
	ds_write_b128 v115, v[64:67] offset:25856
	v_pk_add_f32 v[64:65], v[130:131], v[128:129] neg_lo:[0,1] neg_hi:[0,1]
	v_pk_add_f32 v[66:67], v[132:133], v[128:129] neg_lo:[0,1] neg_hi:[0,1]

; template <bool DUAL>
; __device__ __forceinline__ void rwkv_tile(const Params& p, int l, int tile, unsigned char* smem) {
;     ...
;         dst[0] = u + m0.x * (a - u) + m1.x * (n - u);
;         u = __uint_as_float(uc.x & 0xffff0000u); a = __uint_as_float(up.x & 0xffff0000u); n = __uint_as_float(un.x & 0xffff0000u);
;         dst[1] = u + m0.y * (a - u) + m1.y * (n - u);
;         u = __uint_as_float(uc.y << 16); a = __uint_as_float(up.y << 16); n = __uint_as_float(un.y << 16);
;         dst[2] = u + m0.z * (a - u) + m1.z * (n - u);
	v_pk_fma_f32 v[64:65], v[12:13], v[64:65], v[128:129]
	v_mov_b32_e32 v72, v117

; template <bool DUAL>
; __device__ __forceinline__ void rwkv_tile(const Params& p, int l, int tile, unsigned char* smem) {
;     ...
;         dst[0] = u + m0.x * (a - u) + m1.x * (n - u);
;         u = __uint_as_float(uc.x & 0xffff0000u); a = __uint_as_float(up.x & 0xffff0000u); n = __uint_as_float(un.x & 0xffff0000u);
;         dst[1] = u + m0.y * (a - u) + m1.y * (n - u);
;         u = __uint_as_float(uc.y << 16); a = __uint_as_float(up.y << 16); n = __uint_as_float(un.y << 16);
;         dst[2] = u + m0.z * (a - u) + m1.z * (n - u);
;         u = __uint_as_float(uc.y & 0xffff0000u); a = __uint_as_float(up.y & 0xffff0000u); n = __uint_as_float(un.y & 0xffff0000u);
;         dst[3] = u + m0.w * (a - u) + m1.w * (n - u);
;       }
;       const uint2 ue = *(const uint2*)(q0), ua = *(const uint2*)(q0 + 64), uk = *(const uint2*)(q0 + 128);
;       const float ew[4] = {__uint_as_float(ue.x << 16), __uint_as_float(ue.x & 0xffff0000u), __uint_as_float(ue.y << 16), __uint_as_float(ue.y & 0xffff0000u)};
;       const float av[4] = {__uint_as_float(ua.x << 16), __uint_as_float(ua.x & 0xffff0000u), __uint_as_float(ua.y << 16), __uint_as_float(ua.y & 0xffff0000u)};
;       const float kk[4] = {__uint_as_float(uk.x << 16), __uint_as_float(uk.x & 0xffff0000u), __uint_as_float(uk.y << 16), __uint_as_float(uk.y & 0xffff0000u)};
;       const float kav[4] = {ka4.x, ka4.y, ka4.z, ka4.w};
;       float4 o0, o1, o2, o3, o4, o5;
;       float* f0 = (float*)&o0; float* f1 = (float*)&o1; float* f2 = (float*)&o2; float* f3 = (float*)&o3; float* f4 = (float*)&o4; float* f5 = (float*)&o5;
; #pragma unroll
;       for (int e = 0; e < 4; ++e) {
;         f0[e] = __expf(-ew[e]);
;         f1[e] = kk[e];
;         f2[e] = kk[e] * av[e];
;         f3[e] = ksv[e] * (1.f + (av[e] - 1.f) * kav[e]);
	v_pk_fma_f32 v[64:65], v[20:21], v[66:67], v[64:65]
	v_pk_add_f32 v[66:67], v[72:73], -1.0 op_sel_hi:[1,0]
	v_lshlrev_b32_e32 v80, 16, v81
	v_and_b32_e32 v81, 0xffff0000, v81

; template <bool DUAL>
; __device__ __forceinline__ void rwkv_tile(const Params& p, int l, int tile, unsigned char* smem) {
;     ...
;         dst[0] = u + m0.x * (a - u) + m1.x * (n - u);
;         u = __uint_as_float(uc.x & 0xffff0000u); a = __uint_as_float(up.x & 0xffff0000u); n = __uint_as_float(un.x & 0xffff0000u);
;         dst[1] = u + m0.y * (a - u) + m1.y * (n - u);
;         u = __uint_as_float(uc.y << 16); a = __uint_as_float(up.y << 16); n = __uint_as_float(un.y << 16);
;         dst[2] = u + m0.z * (a - u) + m1.z * (n - u);
;         u = __uint_as_float(uc.y & 0xffff0000u); a = __uint_as_float(up.y & 0xffff0000u); n = __uint_as_float(un.y & 0xffff0000u);
;         dst[3] = u + m0.w * (a - u) + m1.w * (n - u);
;       }
;       const uint2 ue = *(const uint2*)(q0), ua = *(const uint2*)(q0 + 64), uk = *(const uint2*)(q0 + 128);
;       const float ew[4] = {__uint_as_float(ue.x << 16), __uint_as_float(ue.x & 0xffff0000u), __uint_as_float(ue.y << 16), __uint_as_float(ue.y & 0xffff0000u)};
;       const float av[4] = {__uint_as_float(ua.x << 16), __uint_as_float(ua.x & 0xffff0000u), __uint_as_float(ua.y << 16), __uint_as_float(ua.y & 0xffff0000u)};
;       const float kk[4] = {__uint_as_float(uk.x << 16), __uint_as_float(uk.x & 0xffff0000u), __uint_as_float(uk.y << 16), __uint_as_float(uk.y & 0xffff0000u)};
;       const float kav[4] = {ka4.x, ka4.y, ka4.z, ka4.w};
;       float4 o0, o1, o2, o3, o4, o5;
;       float* f0 = (float*)&o0; float* f1 = (float*)&o1; float* f2 = (float*)&o2; float* f3 = (float*)&o3; float* f4 = (float*)&o4; float* f5 = (float*)&o5;
; #pragma unroll
;       for (int e = 0; e < 4; ++e) {
;         f0[e] = __expf(-ew[e]);
;         f1[e] = kk[e];
;         f2[e] = kk[e] * av[e];
;         f3[e] = ksv[e] * (1.f + (av[e] - 1.f) * kav[e]);
;         f4[e] = rs[e];
;         f5[e] = vs[e];
;       }
;       float* rp = rec + i * 384 + lc;
;       *(float4*)(rp) = o0; *(float4*)(rp + 64) = o1; *(float4*)(rp + 128) = o2;
;       *(float4*)(rp + 192) = o3; *(float4*)(rp + 256) = o4; *(float4*)(rp + 320) = o5;
	v_pk_fma_f32 v[66:67], v[24:25], v[66:67], 1.0 op_sel_hi:[1,1,0]
	v_pk_add_f32 v[68:69], v[136:137], v[134:135] neg_lo:[0,1] neg_hi:[0,1]
	v_pk_mul_f32 v[64:65], v[64:65], v[66:67]
	v_pk_add_f32 v[66:67], v[80:81], v[134:135] neg_lo:[0,1] neg_hi:[0,1]
	v_mov_b32_e32 v146, v149
	v_pk_fma_f32 v[66:67], v[14:15], v[66:67], v[134:135]
	v_lshlrev_b32_e32 v120, 16, v76
	v_pk_fma_f32 v[66:67], v[22:23], v[68:69], v[66:67]
	v_pk_add_f32 v[68:69], v[146:147], -1.0 op_sel_hi:[1,0]
	v_and_b32_e32 v121, 0xffff0000, v76
	v_pk_fma_f32 v[68:69], v[26:27], v[68:69], 1.0 op_sel_hi:[1,1,0]
	v_lshlrev_b32_e32 v76, 16, v77
	v_pk_mul_f32 v[66:67], v[66:67], v[68:69]
	ds_write_b128 v115, v[64:67] offset:26112
	v_pk_add_f32 v[64:65], v[120:121], v[78:79] neg_lo:[0,1] neg_hi:[0,1]
	v_and_b32_e32 v77, 0xffff0000, v77
	v_pk_fma_f32 v[64:65], v[8:9], v[64:65], v[78:79]
	v_pk_add_f32 v[66:67], v[122:123], v[78:79] neg_lo:[0,1] neg_hi:[0,1]
	v_pk_add_f32 v[68:69], v[126:127], v[124:125] neg_lo:[0,1] neg_hi:[0,1]
	v_pk_fma_f32 v[64:65], v[0:1], v[66:67], v[64:65]
	v_pk_add_f32 v[66:67], v[76:77], v[124:125] neg_lo:[0,1] neg_hi:[0,1]
	v_lshlrev_b32_e32 v140, 16, v82
	v_pk_fma_f32 v[66:67], v[10:11], v[66:67], v[124:125]
	v_and_b32_e32 v141, 0xffff0000, v82
	v_pk_fma_f32 v[66:67], v[2:3], v[68:69], v[66:67]
	v_lshlrev_b32_e32 v142, 16, v74
	v_and_b32_e32 v143, 0xffff0000, v74
	ds_write_b128 v115, v[64:67] offset:26368
	v_pk_add_f32 v[64:65], v[140:141], v[138:139] neg_lo:[0,1] neg_hi:[0,1]
	v_lshlrev_b32_e32 v82, 16, v83
	v_and_b32_e32 v83, 0xffff0000, v83
	v_pk_fma_f32 v[64:65], v[4:5], v[64:65], v[138:139]
	v_pk_add_f32 v[66:67], v[142:143], v[138:139] neg_lo:[0,1] neg_hi:[0,1]
	v_lshlrev_b32_e32 v74, 16, v75
	v_and_b32_e32 v75, 0xffff0000, v75
	v_pk_fma_f32 v[64:65], v[16:17], v[66:67], v[64:65]
	v_pk_add_f32 v[66:67], v[82:83], v[144:145] neg_lo:[0,1] neg_hi:[0,1]
	v_pk_add_f32 v[68:69], v[74:75], v[144:145] neg_lo:[0,1] neg_hi:[0,1]
	v_pk_fma_f32 v[66:67], v[6:7], v[66:67], v[144:145]
	s_add_i32 s56, s28, 1
	v_pk_fma_f32 v[66:67], v[18:19], v[68:69], v[66:67]
	ds_write_b128 v115, v[64:67] offset:26624
	ds_read2_b64 v[64:67], v109 offset1:16
	ds_read_b64 v[76:77], v110
	ds_read2_b64 v[68:71], v109 offset0:32 offset1:48
	ds_read_b64 v[80:81], v111
	ds_read_b64 v[82:83], v112
	ds_read_b64 v[118:119], v113 offset:12928
	ds_read2_b64 v[72:75], v109 offset0:64 offset1:80
	s_waitcnt lgkmcnt(6)
	v_lshlrev_b32_e32 v78, 16, v64
	v_and_b32_e32 v79, 0xffff0000, v64
	v_add_u32_e32 v64, 0x3000, v113
	v_lshlrev_b32_e32 v124, 16, v65
	v_and_b32_e32 v125, 0xffff0000, v65
	v_lshlrev_b32_e32 v128, 16, v66
	v_and_b32_e32 v129, 0xffff0000, v66
	v_lshlrev_b32_e32 v134, 16, v67
	v_and_b32_e32 v135, 0xffff0000, v67
	ds_read2_b64 v[64:67], v64 offset0:48 offset1:64
	s_waitcnt lgkmcnt(5)
	v_lshlrev_b32_e32 v138, 16, v68
	v_and_b32_e32 v139, 0xffff0000, v68
	s_waitcnt lgkmcnt(1)
	v_lshlrev_b32_e32 v132, 16, v72
	v_and_b32_e32 v133, 0xffff0000, v72
	s_waitcnt lgkmcnt(0)
; template <bool DUAL>
; __device__ __forceinline__ void rwkv_tile(const Params& p, int l, int tile, unsigned char* smem) {
;     ...
;     for (int k = 0; k < 2; ++k) {
;       const int i = (tid >> 4) + 16 * k;
;       const int ri = (d == 0) ? i + 1 : 32 - i;
;       const bf16_t* r0 = raw + ri * 192 + lc;
;       const bf16_t* q0 = pre + (ri - 1) * 192 + lc;
;       float rs[4], ksv[4], vs[4];
; #pragma unroll
;       for (int sl = 0; sl < 3; ++sl) {
;         const uint2 uc = *(const uint2*)(r0 + sl * 64), up = *(const uint2*)(r0 + sl * 64 - 192), un = *(const uint2*)(r0 + sl * 64 + 192);
;         const float4 m0 = (sl == 0) ? m0r : ((sl == 1) ? m0k : m0v);
;         const float4 m1 = (sl == 0) ? m1r : ((sl == 1) ? m1k : m1v);
;         float* dst = (sl == 0) ? rs : ((sl == 1) ? ksv : vs);
;         float u, a, n;
;         u = __uint_as_float(uc.x << 16); a = __uint_as_float(up.x << 16); n = __uint_as_float(un.x << 16);
;         dst[0] = u + m0.x * (a - u) + m1.x * (n - u);
;         u = __uint_as_float(uc.x & 0xffff0000u); a = __uint_as_float(up.x & 0xffff0000u); n = __uint_as_float(un.x & 0xffff0000u);
;         dst[1] = u + m0.y * (a - u) + m1.y * (n - u);
;         u = __uint_as_float(uc.y << 16); a = __uint_as_float(up.y << 16); n = __uint_as_float(un.y << 16);
;         dst[2] = u + m0.z * (a - u) + m1.z * (n - u);
;         u = __uint_as_float(uc.y & 0xffff0000u); a = __uint_as_float(up.y & 0xffff0000u); n = __uint_as_float(un.y & 0xffff0000u);
;         dst[3] = u + m0.w * (a - u) + m1.w * (n - u);
;       }
;       const uint2 ue = *(const uint2*)(q0), ua = *(const uint2*)(q0 + 64), uk = *(const uint2*)(q0 + 128);
;       const float ew[4] = {__uint_as_float(ue.x << 16), __uint_as_float(ue.x & 0xffff0000u), __uint_as_float(ue.y << 16), __uint_as_float(ue.y & 0xffff0000u)};
;       const float av[4] = {__uint_as_float(ua.x << 16), __uint_as_float(ua.x & 0xffff0000u), __uint_as_float(ua.y << 16), __uint_as_float(ua.y & 0xffff0000u)};
;       const float kk[4] = {__uint_as_float(uk.x << 16), __uint_as_float(uk.x & 0xffff0000u), __uint_as_float(uk.y << 16), __uint_as_float(uk.y & 0xffff0000u)};
;       const float kav[4] = {ka4.x, ka4.y, ka4.z, ka4.w};
;       float4 o0, o1, o2, o3, o4, o5;
;       float* f0 = (float*)&o0; float* f1 = (float*)&o1; float* f2 = (float*)&o2; float* f3 = (float*)&o3; float* f4 = (float*)&o4; float* f5 = (float*)&o5;
	v_lshlrev_b32_e32 v68, 16, v64
	v_and_b32_e32 v64, 0xffff0000, v64
	v_lshlrev_b32_e32 v72, 16, v65
	v_mul_f32_e32 v64, 0xbfb8aa3b, v64
	v_lshlrev_b32_e32 v126, 16, v71
	v_and_b32_e32 v127, 0xffff0000, v71
	v_and_b32_e32 v65, 0xffff0000, v65
	v_exp_f32_e32 v71, v64
	v_mul_f32_e32 v64, 0xbfb8aa3b, v72
	v_mul_f32_e32 v68, 0xbfb8aa3b, v68
	v_exp_f32_e32 v72, v64
	v_mul_f32_e32 v64, 0xbfb8aa3b, v65
	v_lshlrev_b32_e32 v122, 16, v70
	v_and_b32_e32 v123, 0xffff0000, v70
	v_lshlrev_b32_e32 v136, 16, v73
	v_and_b32_e32 v137, 0xffff0000, v73
	v_exp_f32_e32 v70, v68
	v_exp_f32_e32 v73, v64
	v_lshlrev_b32_e32 v117, 16, v66
	v_lshlrev_b32_e32 v146, 16, v119
	v_lshlrev_b32_e32 v149, 16, v67
	ds_write_b128 v115, v[70:73] offset:49920
	v_and_b32_e32 v71, 16, v66
	v_and_b32_e32 v70, 0xffff0000, v118
	v_lshlrev_b32_e32 v72, 16, v118
	v_and_b32_e32 v73, 0xffff0000, v66
	v_pk_mov_b32 v[64:65], v[116:117], v[70:71] op_sel:[1,0]
	v_and_b32_e32 v151, 16, v67
	v_and_b32_e32 v150, 0xffff0000, v119
	v_lshlrev_b32_e32 v130, 16, v80
	v_and_b32_e32 v131, 0xffff0000, v80
	v_lshlrev_b32_e32 v144, 16, v69
	v_and_b32_e32 v145, 0xffff0000, v69
	v_pk_mul_f32 v[64:65], v[72:73], v[64:65]
	v_and_b32_e32 v147, 0xffff0000, v67
	v_pk_mov_b32 v[66:67], v[148:149], v[150:151] op_sel:[1,0]
	v_mov_b32_e32 v68, v72
	v_mov_b32_e32 v69, v70
	v_mov_b32_e32 v70, v146
	v_mov_b32_e32 v71, v150
	v_pk_mul_f32 v[66:67], v[146:147], v[66:67]
	ds_write_b128 v115, v[68:71] offset:50176
	ds_write_b128 v115, v[64:67] offset:50432
	v_pk_add_f32 v[64:65], v[130:131], v[128:129] neg_lo:[0,1] neg_hi:[0,1]
	v_pk_add_f32 v[66:67], v[132:133], v[128:129] neg_lo:[0,1] neg_hi:[0,1]
	v_pk_fma_f32 v[64:65], v[12:13], v[64:65], v[128:129]
	v_mov_b32_e32 v72, v117
	v_pk_fma_f32 v[64:65], v[20:21], v[66:67], v[64:65]
	v_pk_add_f32 v[66:67], v[72:73], -1.0 op_sel_hi:[1,0]
	v_lshlrev_b32_e32 v80, 16, v81
	v_and_b32_e32 v81, 0xffff0000, v81
	v_pk_fma_f32 v[66:67], v[24:25], v[66:67], 1.0 op_sel_hi:[1,1,0]
	v_pk_add_f32 v[68:69], v[136:137], v[134:135] neg_lo:[0,1] neg_hi:[0,1]
	v_pk_mul_f32 v[64:65], v[64:65], v[66:67]
	v_pk_add_f32 v[66:67], v[80:81], v[134:135] neg_lo:[0,1] neg_hi:[0,1]
	v_mov_b32_e32 v146, v149
	v_pk_fma_f32 v[66:67], v[14:15], v[66:67], v[134:135]
	v_lshlrev_b32_e32 v120, 16, v76
	v_pk_fma_f32 v[66:67], v[22:23], v[68:69], v[66:67]
	v_pk_add_f32 v[68:69], v[146:147], -1.0 op_sel_hi:[1,0]
	v_and_b32_e32 v121, 0xffff0000, v76
	v_pk_fma_f32 v[68:69], v[26:27], v[68:69], 1.0 op_sel_hi:[1,1,0]
	v_lshlrev_b32_e32 v76, 16, v77
	v_pk_mul_f32 v[66:67], v[66:67], v[68:69]
	ds_write_b128 v115, v[64:67] offset:50688
	v_pk_add_f32 v[64:65], v[120:121], v[78:79] neg_lo:[0,1] neg_hi:[0,1]
	v_and_b32_e32 v77, 0xffff0000, v77
	v_pk_fma_f32 v[64:65], v[8:9], v[64:65], v[78:79]
	v_pk_add_f32 v[66:67], v[122:123], v[78:79] neg_lo:[0,1] neg_hi:[0,1]
	v_pk_add_f32 v[68:69], v[126:127], v[124:125] neg_lo:[0,1] neg_hi:[0,1]
	v_pk_fma_f32 v[64:65], v[0:1], v[66:67], v[64:65]
	v_pk_add_f32 v[66:67], v[76:77], v[124:125] neg_lo:[0,1] neg_hi:[0,1]
	v_lshlrev_b32_e32 v140, 16, v82
	v_pk_fma_f32 v[66:67], v[10:11], v[66:67], v[124:125]
	v_and_b32_e32 v141, 0xffff0000, v82
	v_pk_fma_f32 v[66:67], v[2:3], v[68:69], v[66:67]
	v_lshlrev_b32_e32 v142, 16, v74
	v_and_b32_e32 v143, 0xffff0000, v74
	ds_write_b128 v115, v[64:67] offset:50944
	v_pk_add_f32 v[64:65], v[140:141], v[138:139] neg_lo:[0,1] neg_hi:[0,1]
	v_readlane_b32 s0, v254, 14
	v_lshlrev_b32_e32 v82, 16, v83
	v_and_b32_e32 v83, 0xffff0000, v83
	v_pk_fma_f32 v[64:65], v[4:5], v[64:65], v[138:139]
	v_pk_add_f32 v[66:67], v[142:143], v[138:139] neg_lo:[0,1] neg_hi:[0,1]
	s_cmp_lt_u32 s56, s0
	v_lshlrev_b32_e32 v74, 16, v75
	v_and_b32_e32 v75, 0xffff0000, v75
	v_pk_fma_f32 v[64:65], v[16:17], v[66:67], v[64:65]
	v_pk_add_f32 v[66:67], v[82:83], v[144:145] neg_lo:[0,1] neg_hi:[0,1]
	s_cselect_b64 s[54:55], -1, 0
	s_cmp_ge_u32 s56, s0
	v_pk_fma_f32 v[66:67], v[6:7], v[66:67], v[144:145]
	v_pk_add_f32 v[68:69], v[74:75], v[144:145] neg_lo:[0,1] neg_hi:[0,1]
	s_cselect_b64 s[52:53], -1, 0
	v_pk_fma_f32 v[66:67], v[18:19], v[68:69], v[66:67]
	s_and_b64 vcc, exec, s[52:53]
	ds_write_b128 v115, v[64:67] offset:51200
	s_waitcnt lgkmcnt(0)
	s_barrier
